# spatial gating sample tiles: osgu store address in its own register pair so LN gamma/beta are not reloaded after every chunk (7 round trips per sample unit removed)
# baseline (speedup 1.0000x reference)
.LBB0_709:
	s_or_b64 exec, exec, s[4:5]
	s_lshl_b32 s4, s44, 8
	v_or_b32_e32 v44, s4, v137
	v_lshlrev_b32_e32 v144, 2, v44
	s_waitcnt lgkmcnt(0)
	s_barrier
	global_load_dwordx4 v[60:63], v144, s[12:13]
	global_load_dwordx4 v[48:51], v144, s[10:11]
	global_load_dwordx4 v[44:47], v144, s[10:11] offset:16
	global_load_dwordx4 v[56:59], v144, s[12:13] offset:16
	ds_read_b64 v[80:81], v138
	v_lshlrev_b32_e32 v82, 16, v76
	v_and_b32_e32 v83, 0xffff0000, v76
	v_lshlrev_b32_e32 v76, 16, v77
	v_and_b32_e32 v77, 0xffff0000, v77
	v_lshlrev_b32_e32 v88, 16, v78
	v_and_b32_e32 v89, 0xffff0000, v78
	v_lshlrev_b32_e32 v78, 16, v79
	v_and_b32_e32 v79, 0xffff0000, v79
	s_waitcnt lgkmcnt(0)
	v_pk_add_f32 v[82:83], v[82:83], v[80:81] op_sel_hi:[1,0] neg_lo:[0,1] neg_hi:[0,1]
	v_pk_add_f32 v[76:77], v[76:77], v[80:81] op_sel_hi:[1,0] neg_lo:[0,1] neg_hi:[0,1]
	v_pk_add_f32 v[88:89], v[88:89], v[80:81] op_sel_hi:[1,0] neg_lo:[0,1] neg_hi:[0,1]
	v_pk_add_f32 v[78:79], v[78:79], v[80:81] op_sel_hi:[1,0] neg_lo:[0,1] neg_hi:[0,1]
	v_pk_mul_f32 v[82:83], v[80:81], v[82:83] op_sel:[1,0]
	v_pk_mul_f32 v[76:77], v[80:81], v[76:77] op_sel:[1,0]
	v_pk_mul_f32 v[88:89], v[80:81], v[88:89] op_sel:[1,0]
	v_pk_mul_f32 v[78:79], v[80:81], v[78:79] op_sel:[1,0]
	v_cndmask_b32_e64 v84, 0, 1, s[40:41]
	s_add_i32 s5, s43, 0xffffc000
	v_cmp_ne_u32_e64 s[38:39], 1, v84
	v_lshl_add_u64 v[86:87], s[10:11], 0, v[144:145]
	v_lshl_add_u64 v[84:85], s[12:13], 0, v[144:145]
	s_andn2_b64 vcc, exec, s[40:41]
	s_waitcnt vmcnt(2)
	v_pk_fma_f32 v[80:81], v[48:49], v[82:83], v[60:61]
	v_pk_fma_f32 v[82:83], v[50:51], v[76:77], v[62:63]
	s_waitcnt vmcnt(0)
	v_pk_fma_f32 v[76:77], v[44:45], v[88:89], v[56:57]
	v_pk_fma_f32 v[78:79], v[46:47], v[78:79], v[58:59]
	v_cvt_pk_bf16_f32 v88, v80, v81
	v_cvt_pk_bf16_f32 v89, v82, v83
	v_cvt_pk_bf16_f32 v90, v76, v77
	v_cvt_pk_bf16_f32 v91, v78, v79
	ds_write_b128 v169, v[88:91]
	s_cbranch_vccnz .LBB0_711
	v_add_u32_e32 v232, s5, v129
	v_ashrrev_i32_e32 v233, 31, v232
	v_lshlrev_b64 v[232:233], 13, v[232:233]
	v_lshl_add_u64 v[232:233], s[24:25], 0, v[232:233]
	v_lshl_add_u64 v[232:233], v[232:233], 0, v[144:145]
	global_store_dwordx4 v[232:233], v[80:83], off
	global_store_dwordx4 v[232:233], v[76:79], off offset:16
	s_nop 2
.LBB0_711:
	ds_read_b64 v[80:81], v139
	v_lshlrev_b32_e32 v76, 16, v72
	v_and_b32_e32 v77, 0xffff0000, v72
	v_lshlrev_b32_e32 v72, 16, v73
	v_and_b32_e32 v73, 0xffff0000, v73
	s_waitcnt lgkmcnt(0)
	v_pk_add_f32 v[72:73], v[72:73], v[80:81] op_sel_hi:[1,0] neg_lo:[0,1] neg_hi:[0,1]
	v_pk_add_f32 v[76:77], v[76:77], v[80:81] op_sel_hi:[1,0] neg_lo:[0,1] neg_hi:[0,1]
	v_pk_mul_f32 v[72:73], v[80:81], v[72:73] op_sel:[1,0]
	v_pk_mul_f32 v[76:77], v[80:81], v[76:77] op_sel:[1,0]
	v_pk_fma_f32 v[78:79], v[50:51], v[72:73], v[62:63]
	v_lshlrev_b32_e32 v72, 16, v74
	v_and_b32_e32 v73, 0xffff0000, v74
	v_lshlrev_b32_e32 v74, 16, v75
	v_and_b32_e32 v75, 0xffff0000, v75
	v_pk_add_f32 v[72:73], v[72:73], v[80:81] op_sel_hi:[1,0] neg_lo:[0,1] neg_hi:[0,1]
	v_pk_add_f32 v[74:75], v[74:75], v[80:81] op_sel_hi:[1,0] neg_lo:[0,1] neg_hi:[0,1]
	v_pk_mul_f32 v[72:73], v[80:81], v[72:73] op_sel:[1,0]
	v_pk_mul_f32 v[74:75], v[80:81], v[74:75] op_sel:[1,0]
	v_pk_fma_f32 v[76:77], v[48:49], v[76:77], v[60:61]
	v_pk_fma_f32 v[72:73], v[44:45], v[72:73], v[56:57]
	v_pk_fma_f32 v[74:75], v[46:47], v[74:75], v[58:59]
	v_cvt_pk_bf16_f32 v80, v76, v77
	v_cvt_pk_bf16_f32 v81, v78, v79
	v_cvt_pk_bf16_f32 v82, v72, v73
	v_cvt_pk_bf16_f32 v83, v74, v75
	s_and_b64 vcc, exec, s[38:39]
	ds_write_b128 v170, v[80:83]
	s_cbranch_vccnz .LBB0_713
	v_add_u32_e32 v232, s5, v130
	v_ashrrev_i32_e32 v233, 31, v232
	v_lshlrev_b64 v[232:233], 13, v[232:233]
	v_lshl_add_u64 v[232:233], s[24:25], 0, v[232:233]
	v_lshl_add_u64 v[232:233], v[232:233], 0, v[144:145]
	global_store_dwordx4 v[232:233], v[76:79], off
	global_store_dwordx4 v[232:233], v[72:75], off offset:16
	s_nop 2
.LBB0_713:
	ds_read_b64 v[76:77], v140
	v_lshlrev_b32_e32 v72, 16, v68
	v_and_b32_e32 v73, 0xffff0000, v68
	v_lshlrev_b32_e32 v68, 16, v69
	v_and_b32_e32 v69, 0xffff0000, v69
	s_waitcnt lgkmcnt(0)
	v_pk_add_f32 v[68:69], v[68:69], v[76:77] op_sel_hi:[1,0] neg_lo:[0,1] neg_hi:[0,1]
	v_pk_add_f32 v[72:73], v[72:73], v[76:77] op_sel_hi:[1,0] neg_lo:[0,1] neg_hi:[0,1]
	v_pk_mul_f32 v[68:69], v[76:77], v[68:69] op_sel:[1,0]
	v_pk_mul_f32 v[72:73], v[76:77], v[72:73] op_sel:[1,0]
	v_pk_fma_f32 v[74:75], v[50:51], v[68:69], v[62:63]
	v_lshlrev_b32_e32 v68, 16, v70
	v_and_b32_e32 v69, 0xffff0000, v70
	v_lshlrev_b32_e32 v70, 16, v71
	v_and_b32_e32 v71, 0xffff0000, v71
	v_pk_add_f32 v[68:69], v[68:69], v[76:77] op_sel_hi:[1,0] neg_lo:[0,1] neg_hi:[0,1]
	v_pk_add_f32 v[70:71], v[70:71], v[76:77] op_sel_hi:[1,0] neg_lo:[0,1] neg_hi:[0,1]
	v_pk_mul_f32 v[68:69], v[76:77], v[68:69] op_sel:[1,0]
	v_pk_mul_f32 v[70:71], v[76:77], v[70:71] op_sel:[1,0]
	v_pk_fma_f32 v[72:73], v[48:49], v[72:73], v[60:61]
	v_pk_fma_f32 v[68:69], v[44:45], v[68:69], v[56:57]
	v_pk_fma_f32 v[70:71], v[46:47], v[70:71], v[58:59]
	v_cvt_pk_bf16_f32 v76, v72, v73
	v_cvt_pk_bf16_f32 v77, v74, v75
	v_cvt_pk_bf16_f32 v78, v68, v69
	v_cvt_pk_bf16_f32 v79, v70, v71
	s_and_b64 vcc, exec, s[38:39]
	ds_write_b128 v171, v[76:79]
	s_cbranch_vccnz .LBB0_715
	v_add_u32_e32 v232, s5, v131
	v_ashrrev_i32_e32 v233, 31, v232
	v_lshlrev_b64 v[232:233], 13, v[232:233]
	v_lshl_add_u64 v[232:233], s[24:25], 0, v[232:233]
	v_lshl_add_u64 v[232:233], v[232:233], 0, v[144:145]
	global_store_dwordx4 v[232:233], v[72:75], off
	global_store_dwordx4 v[232:233], v[68:71], off offset:16
	s_nop 2
.LBB0_715:
	ds_read_b64 v[72:73], v141
	v_lshlrev_b32_e32 v68, 16, v64
	v_and_b32_e32 v69, 0xffff0000, v64
	v_lshlrev_b32_e32 v64, 16, v65
	v_and_b32_e32 v65, 0xffff0000, v65
	s_waitcnt lgkmcnt(0)
	v_pk_add_f32 v[64:65], v[64:65], v[72:73] op_sel_hi:[1,0] neg_lo:[0,1] neg_hi:[0,1]
	v_pk_add_f32 v[68:69], v[68:69], v[72:73] op_sel_hi:[1,0] neg_lo:[0,1] neg_hi:[0,1]
	v_pk_mul_f32 v[64:65], v[72:73], v[64:65] op_sel:[1,0]
	v_pk_mul_f32 v[68:69], v[72:73], v[68:69] op_sel:[1,0]
	v_pk_fma_f32 v[70:71], v[50:51], v[64:65], v[62:63]
	v_lshlrev_b32_e32 v64, 16, v66
	v_and_b32_e32 v65, 0xffff0000, v66
	v_lshlrev_b32_e32 v66, 16, v67
	v_and_b32_e32 v67, 0xffff0000, v67
	v_pk_add_f32 v[64:65], v[64:65], v[72:73] op_sel_hi:[1,0] neg_lo:[0,1] neg_hi:[0,1]
	v_pk_add_f32 v[66:67], v[66:67], v[72:73] op_sel_hi:[1,0] neg_lo:[0,1] neg_hi:[0,1]
	v_pk_mul_f32 v[64:65], v[72:73], v[64:65] op_sel:[1,0]
	v_pk_mul_f32 v[66:67], v[72:73], v[66:67] op_sel:[1,0]
	v_pk_fma_f32 v[68:69], v[48:49], v[68:69], v[60:61]
	v_pk_fma_f32 v[64:65], v[44:45], v[64:65], v[56:57]
	v_pk_fma_f32 v[66:67], v[46:47], v[66:67], v[58:59]
	v_cvt_pk_bf16_f32 v72, v68, v69
	v_cvt_pk_bf16_f32 v73, v70, v71
	v_cvt_pk_bf16_f32 v74, v64, v65
	v_cvt_pk_bf16_f32 v75, v66, v67
	s_and_b64 vcc, exec, s[38:39]
	ds_write_b128 v172, v[72:75]
	s_cbranch_vccnz .LBB0_717
	v_add_u32_e32 v232, s5, v132
	v_ashrrev_i32_e32 v233, 31, v232
	v_lshlrev_b64 v[232:233], 13, v[232:233]
	v_lshl_add_u64 v[232:233], s[24:25], 0, v[232:233]
	v_lshl_add_u64 v[232:233], v[232:233], 0, v[144:145]
	global_store_dwordx4 v[232:233], v[68:71], off
	global_store_dwordx4 v[232:233], v[64:67], off offset:16
	s_nop 2
.LBB0_717:
	ds_read_b64 v[68:69], v142
	v_lshlrev_b32_e32 v64, 16, v52
	v_and_b32_e32 v65, 0xffff0000, v52
	v_lshlrev_b32_e32 v52, 16, v53
	v_and_b32_e32 v53, 0xffff0000, v53
	s_waitcnt lgkmcnt(0)
	v_pk_add_f32 v[52:53], v[52:53], v[68:69] op_sel_hi:[1,0] neg_lo:[0,1] neg_hi:[0,1]
	v_pk_add_f32 v[64:65], v[64:65], v[68:69] op_sel_hi:[1,0] neg_lo:[0,1] neg_hi:[0,1]
	v_pk_mul_f32 v[52:53], v[68:69], v[52:53] op_sel:[1,0]
	v_pk_mul_f32 v[64:65], v[68:69], v[64:65] op_sel:[1,0]
	v_pk_fma_f32 v[66:67], v[50:51], v[52:53], v[62:63]
	v_lshlrev_b32_e32 v52, 16, v54
	v_and_b32_e32 v53, 0xffff0000, v54
	v_lshlrev_b32_e32 v54, 16, v55
	v_and_b32_e32 v55, 0xffff0000, v55
	v_pk_add_f32 v[52:53], v[52:53], v[68:69] op_sel_hi:[1,0] neg_lo:[0,1] neg_hi:[0,1]
	v_pk_add_f32 v[54:55], v[54:55], v[68:69] op_sel_hi:[1,0] neg_lo:[0,1] neg_hi:[0,1]
	v_pk_mul_f32 v[52:53], v[68:69], v[52:53] op_sel:[1,0]
	v_pk_mul_f32 v[54:55], v[68:69], v[54:55] op_sel:[1,0]
	v_pk_fma_f32 v[64:65], v[48:49], v[64:65], v[60:61]
	v_pk_fma_f32 v[52:53], v[44:45], v[52:53], v[56:57]
	v_pk_fma_f32 v[54:55], v[46:47], v[54:55], v[58:59]
	v_cvt_pk_bf16_f32 v68, v64, v65
	v_cvt_pk_bf16_f32 v69, v66, v67
	v_cvt_pk_bf16_f32 v70, v52, v53
	v_cvt_pk_bf16_f32 v71, v54, v55
	s_and_b64 vcc, exec, s[38:39]
	ds_write_b128 v173, v[68:71]
	s_cbranch_vccnz .LBB0_719
	v_add_u32_e32 v232, s5, v133
	v_ashrrev_i32_e32 v233, 31, v232
	v_lshlrev_b64 v[232:233], 13, v[232:233]
	v_lshl_add_u64 v[232:233], s[24:25], 0, v[232:233]
	v_lshl_add_u64 v[232:233], v[232:233], 0, v[144:145]
	global_store_dwordx4 v[232:233], v[64:67], off
	global_store_dwordx4 v[232:233], v[52:55], off offset:16
	s_nop 2
.LBB0_719:
	ds_read_b64 v[64:65], v143
	v_lshlrev_b32_e32 v52, 16, v40
	v_and_b32_e32 v53, 0xffff0000, v40
	v_lshlrev_b32_e32 v40, 16, v41
	v_and_b32_e32 v41, 0xffff0000, v41
	s_waitcnt lgkmcnt(0)
	v_pk_add_f32 v[40:41], v[40:41], v[64:65] op_sel_hi:[1,0] neg_lo:[0,1] neg_hi:[0,1]
	v_pk_add_f32 v[52:53], v[52:53], v[64:65] op_sel_hi:[1,0] neg_lo:[0,1] neg_hi:[0,1]
	v_pk_mul_f32 v[40:41], v[64:65], v[40:41] op_sel:[1,0]
	v_pk_mul_f32 v[52:53], v[64:65], v[52:53] op_sel:[1,0]
	v_pk_fma_f32 v[54:55], v[50:51], v[40:41], v[62:63]
	v_lshlrev_b32_e32 v40, 16, v42
	v_and_b32_e32 v41, 0xffff0000, v42
	v_lshlrev_b32_e32 v42, 16, v43
	v_and_b32_e32 v43, 0xffff0000, v43
	v_pk_add_f32 v[40:41], v[40:41], v[64:65] op_sel_hi:[1,0] neg_lo:[0,1] neg_hi:[0,1]
	v_pk_add_f32 v[42:43], v[42:43], v[64:65] op_sel_hi:[1,0] neg_lo:[0,1] neg_hi:[0,1]
	v_pk_mul_f32 v[40:41], v[64:65], v[40:41] op_sel:[1,0]
	v_pk_mul_f32 v[42:43], v[64:65], v[42:43] op_sel:[1,0]
	v_pk_fma_f32 v[52:53], v[48:49], v[52:53], v[60:61]
	v_pk_fma_f32 v[40:41], v[44:45], v[40:41], v[56:57]
	v_pk_fma_f32 v[42:43], v[46:47], v[42:43], v[58:59]
	v_cvt_pk_bf16_f32 v64, v52, v53
	v_cvt_pk_bf16_f32 v65, v54, v55
	v_cvt_pk_bf16_f32 v66, v40, v41
	v_cvt_pk_bf16_f32 v67, v42, v43
	s_and_b64 vcc, exec, s[38:39]
	ds_write_b128 v174, v[64:67]
	s_cbranch_vccnz .LBB0_721
	v_add_u32_e32 v232, s5, v134
	v_ashrrev_i32_e32 v233, 31, v232
	v_lshlrev_b64 v[232:233], 13, v[232:233]
	v_lshl_add_u64 v[232:233], s[24:25], 0, v[232:233]
	v_lshl_add_u64 v[232:233], v[232:233], 0, v[144:145]
	global_store_dwordx4 v[232:233], v[52:55], off
	global_store_dwordx4 v[232:233], v[40:43], off offset:16
	s_nop 2
.LBB0_721:
	ds_read_b64 v[52:53], v159
	v_lshlrev_b32_e32 v40, 16, v36
	v_and_b32_e32 v41, 0xffff0000, v36
	v_lshlrev_b32_e32 v36, 16, v37
	v_and_b32_e32 v37, 0xffff0000, v37
	s_waitcnt lgkmcnt(0)
	v_pk_add_f32 v[36:37], v[36:37], v[52:53] op_sel_hi:[1,0] neg_lo:[0,1] neg_hi:[0,1]
	v_pk_add_f32 v[40:41], v[40:41], v[52:53] op_sel_hi:[1,0] neg_lo:[0,1] neg_hi:[0,1]
	v_pk_mul_f32 v[36:37], v[52:53], v[36:37] op_sel:[1,0]
	v_pk_mul_f32 v[40:41], v[52:53], v[40:41] op_sel:[1,0]
	v_pk_fma_f32 v[42:43], v[50:51], v[36:37], v[62:63]
	v_lshlrev_b32_e32 v36, 16, v38
	v_and_b32_e32 v37, 0xffff0000, v38
	v_lshlrev_b32_e32 v38, 16, v39
	v_and_b32_e32 v39, 0xffff0000, v39
	v_pk_add_f32 v[36:37], v[36:37], v[52:53] op_sel_hi:[1,0] neg_lo:[0,1] neg_hi:[0,1]
	v_pk_add_f32 v[38:39], v[38:39], v[52:53] op_sel_hi:[1,0] neg_lo:[0,1] neg_hi:[0,1]
	v_pk_mul_f32 v[36:37], v[52:53], v[36:37] op_sel:[1,0]
	v_pk_mul_f32 v[38:39], v[52:53], v[38:39] op_sel:[1,0]
	v_pk_fma_f32 v[40:41], v[48:49], v[40:41], v[60:61]
	v_pk_fma_f32 v[36:37], v[44:45], v[36:37], v[56:57]
	v_pk_fma_f32 v[38:39], v[46:47], v[38:39], v[58:59]
	v_cvt_pk_bf16_f32 v52, v40, v41
	v_cvt_pk_bf16_f32 v53, v42, v43
	v_cvt_pk_bf16_f32 v54, v36, v37
	v_cvt_pk_bf16_f32 v55, v38, v39
	s_and_b64 vcc, exec, s[38:39]
	ds_write_b128 v175, v[52:55]
	s_cbranch_vccnz .LBB0_723
	v_add_u32_e32 v232, s5, v135
	v_ashrrev_i32_e32 v233, 31, v232
	v_lshlrev_b64 v[232:233], 13, v[232:233]
	v_lshl_add_u64 v[232:233], s[24:25], 0, v[232:233]
	v_lshl_add_u64 v[232:233], v[232:233], 0, v[144:145]
	global_store_dwordx4 v[232:233], v[40:43], off
	global_store_dwordx4 v[232:233], v[36:39], off offset:16
	s_nop 2
.LBB0_723:
	ds_read_b64 v[40:41], v160
	v_lshlrev_b32_e32 v36, 16, v32
	v_and_b32_e32 v37, 0xffff0000, v32
	v_lshlrev_b32_e32 v32, 16, v33
	v_and_b32_e32 v33, 0xffff0000, v33
	s_waitcnt lgkmcnt(0)
	v_pk_add_f32 v[32:33], v[32:33], v[40:41] op_sel_hi:[1,0] neg_lo:[0,1] neg_hi:[0,1]
	v_pk_add_f32 v[36:37], v[36:37], v[40:41] op_sel_hi:[1,0] neg_lo:[0,1] neg_hi:[0,1]
	v_pk_mul_f32 v[32:33], v[40:41], v[32:33] op_sel:[1,0]
	v_pk_mul_f32 v[36:37], v[40:41], v[36:37] op_sel:[1,0]
	v_pk_fma_f32 v[38:39], v[50:51], v[32:33], v[62:63]
	v_lshlrev_b32_e32 v32, 16, v34
	v_and_b32_e32 v33, 0xffff0000, v34
	v_lshlrev_b32_e32 v34, 16, v35
	v_and_b32_e32 v35, 0xffff0000, v35
	v_pk_add_f32 v[32:33], v[32:33], v[40:41] op_sel_hi:[1,0] neg_lo:[0,1] neg_hi:[0,1]
	v_pk_add_f32 v[34:35], v[34:35], v[40:41] op_sel_hi:[1,0] neg_lo:[0,1] neg_hi:[0,1]
	v_pk_mul_f32 v[32:33], v[40:41], v[32:33] op_sel:[1,0]
	v_pk_mul_f32 v[34:35], v[40:41], v[34:35] op_sel:[1,0]
	v_pk_fma_f32 v[36:37], v[48:49], v[36:37], v[60:61]
	v_pk_fma_f32 v[32:33], v[44:45], v[32:33], v[56:57]
	v_pk_fma_f32 v[34:35], v[46:47], v[34:35], v[58:59]
	v_cvt_pk_bf16_f32 v40, v36, v37
	v_cvt_pk_bf16_f32 v41, v38, v39
	v_cvt_pk_bf16_f32 v42, v32, v33
	v_cvt_pk_bf16_f32 v43, v34, v35
	s_and_b64 vcc, exec, s[38:39]
	v_mov_b32_e32 v111, v121
	v_mov_b32_e32 v113, v127
	v_mov_b32_e32 v178, v126
	v_mov_b32_e32 v179, v125
	v_mov_b32_e32 v180, v124
	v_mov_b32_e32 v181, v123
	v_mov_b32_e32 v182, v122
	v_mov_b32_e32 v183, v118
	ds_write_b128 v176, v[40:43]
	s_cbranch_vccnz .LBB0_704
	v_add_u32_e32 v40, s5, v136
	v_ashrrev_i32_e32 v41, 31, v40
	v_lshlrev_b64 v[40:41], 13, v[40:41]
	v_lshl_add_u64 v[40:41], s[24:25], 0, v[40:41]
	v_lshl_add_u64 v[40:41], v[40:41], 0, v[144:145]
	v_mov_b32_e32 v111, v120
	v_mov_b32_e32 v113, v120
	v_mov_b32_e32 v178, v120
	v_mov_b32_e32 v179, v120
	v_mov_b32_e32 v180, v120
	v_mov_b32_e32 v181, v120
	v_mov_b32_e32 v182, v120
	v_mov_b32_e32 v183, v120
	global_store_dwordx4 v[40:41], v[36:39], off
	global_store_dwordx4 v[40:41], v[32:35], off offset:16
	s_branch .LBB0_704
